# rg_prompt A-fragment conv-row loads prefetched through 18-quad ring, auto-derived vmcnt
# speedup vs baseline: 1.0047x; 1.0047x over previous
.LBB0_193:
	s_xor_b64 s[70:71], s[54:55], -1
	v_readlane_b32 s54, v254, 18
	s_or_b32 s80, s78, s54
	s_lshl_b32 s54, s80, 6
	s_ashr_i32 s55, s54, 31
	s_lshl_b64 s[78:79], s[54:55], 2
	v_readlane_b32 s82, v253, 13
	v_readlane_b32 s83, v253, 14
	s_add_u32 s84, s82, s78
	s_addc_u32 s85, s83, s79
	v_lshlrev_b32_e32 v144, 2, v88
	s_waitcnt lgkmcnt(0)
	v_lshl_add_u64 v[40:41], s[84:85], 0, v[144:145]
	s_movk_i32 s81, 0x1000
	v_add_co_u32_e32 v36, vcc, s81, v40
	s_mov_b64 s[82:83], 0x1000
	s_nop 0
	v_addc_co_u32_e32 v37, vcc, 0, v41, vcc
	v_add_co_u32_e32 v42, vcc, s33, v40
	v_lshl_add_u64 v[0:1], v[40:41], 0, s[82:83]
	s_nop 0
	v_addc_co_u32_e32 v43, vcc, 0, v41, vcc
	s_mov_b64 s[82:83], 0x2000
	global_load_dwordx4 v[8:11], v144, s[84:85] offset:16
	global_load_dwordx4 v[44:47], v144, s[84:85]
	global_load_dwordx4 v[28:31], v[42:43], off offset:-4096
	global_load_dwordx4 v[20:23], v[0:1], off offset:16
	v_lshl_add_u64 v[0:1], v[40:41], 0, s[82:83]
	s_mov_b64 s[82:83], 0x3000
	v_lshl_add_u64 v[12:13], v[40:41], 0, s[82:83]
	s_lshl_b64 s[82:83], s[54:55], 1
	v_add_co_u32_e32 v48, vcc, s87, v40
	v_lshl_add_u64 v[78:79], v[94:95], 0, s[82:83]
	s_nop 0
	v_addc_co_u32_e32 v49, vcc, 0, v41, vcc
	v_lshl_add_u64 v[50:51], v[96:97], 0, s[78:79]
	v_lshl_add_u64 v[38:39], v[78:79], 0, s[58:59]
	global_load_dwordx4 v[4:7], v[42:43], off
	s_nop 0
	global_load_dwordx4 v[0:3], v[0:1], off offset:16
	s_nop 0
	global_load_dwordx4 v[16:19], v[48:49], off
	s_nop 0
	global_load_dwordx4 v[12:15], v[12:13], off offset:16
	s_nop 0
	global_load_dwordx4 v[24:27], v[50:51], off offset:16
	global_load_dwordx4 v[32:35], v[50:51], off
	v_lshl_add_u64 v[38:39], v[78:79], 0, s[60:61]
	v_lshl_add_u64 v[74:75], v[78:79], 0, s[56:57]
	s_mov_b32 s100, 0xffff3a00
	s_mov_b32 s101, -1
	v_lshl_add_u64 v[242:243], v[74:75], 0, s[100:101]
	global_load_dwordx4 v[132:135], v[242:243], off
	s_mov_b32 s100, 0xffff7c00
	s_mov_b32 s101, -1
	v_lshl_add_u64 v[242:243], v[74:75], 0, s[100:101]
	global_load_dwordx4 v[136:139], v[242:243], off
	s_mov_b32 s100, 0xffffbe00
	s_mov_b32 s101, -1
	v_lshl_add_u64 v[242:243], v[74:75], 0, s[100:101]
	global_load_dwordx4 v[140:143], v[242:243], off
	s_mov_b32 s100, 0x0
	s_mov_b32 s101, 0
	v_lshl_add_u64 v[242:243], v[74:75], 0, s[100:101]
	global_load_dwordx4 v[162:165], v[242:243], off
	s_mov_b32 s100, 0x35a00
	s_mov_b32 s101, 0
	v_lshl_add_u64 v[242:243], v[74:75], 0, s[100:101]
	global_load_dwordx4 v[166:169], v[242:243], off
	s_mov_b32 s100, 0x39c00
	s_mov_b32 s101, 0
	v_lshl_add_u64 v[242:243], v[74:75], 0, s[100:101]
	global_load_dwordx4 v[172:175], v[242:243], off
	s_mov_b32 s100, 0x3de00
	s_mov_b32 s101, 0
	v_lshl_add_u64 v[242:243], v[74:75], 0, s[100:101]
	global_load_dwordx4 v[176:179], v[242:243], off
	s_mov_b32 s100, 0x42000
	s_mov_b32 s101, 0
	v_lshl_add_u64 v[242:243], v[74:75], 0, s[100:101]
	global_load_dwordx4 v[180:183], v[242:243], off
	s_mov_b32 s100, 0x77a00
	s_mov_b32 s101, 0
	v_lshl_add_u64 v[242:243], v[74:75], 0, s[100:101]
	global_load_dwordx4 v[184:187], v[242:243], off
	s_mov_b32 s100, 0x7fe00
	s_mov_b32 s101, 0
	v_lshl_add_u64 v[242:243], v[74:75], 0, s[100:101]
	global_load_dwordx4 v[192:195], v[242:243], off
	s_mov_b32 s100, 0x7bc00
	s_mov_b32 s101, 0
	v_lshl_add_u64 v[242:243], v[74:75], 0, s[100:101]
	global_load_dwordx4 v[212:215], v[242:243], off
	s_mov_b32 s100, 0x84000
	s_mov_b32 s101, 0
	v_lshl_add_u64 v[242:243], v[74:75], 0, s[100:101]
	global_load_dwordx4 v[216:219], v[242:243], off
	s_mov_b32 s100, 0xb9a00
	s_mov_b32 s101, 0
	v_lshl_add_u64 v[242:243], v[74:75], 0, s[100:101]
	global_load_dwordx4 v[220:223], v[242:243], off
	s_mov_b32 s100, 0xbdc00
	s_mov_b32 s101, 0
	v_lshl_add_u64 v[242:243], v[74:75], 0, s[100:101]
	global_load_dwordx4 v[224:227], v[242:243], off
	s_mov_b32 s100, 0xc1e00
	s_mov_b32 s101, 0
	v_lshl_add_u64 v[242:243], v[74:75], 0, s[100:101]
	global_load_dwordx4 v[228:231], v[242:243], off
	s_mov_b32 s100, 0xc6000
	s_mov_b32 s101, 0
	v_lshl_add_u64 v[242:243], v[74:75], 0, s[100:101]
	global_load_dwordx4 v[232:235], v[242:243], off
	s_mov_b32 s100, 0xffff3a40
	s_mov_b32 s101, -1
	v_lshl_add_u64 v[242:243], v[74:75], 0, s[100:101]
	global_load_dwordx4 v[236:239], v[242:243], off
	s_mov_b32 s100, 0xffff7c40
	s_mov_b32 s101, -1
	v_lshl_add_u64 v[242:243], v[74:75], 0, s[100:101]
	global_load_dwordx4 v[246:249], v[242:243], off
	s_waitcnt vmcnt(23)
	v_mov_b32_e32 v86, v4
	s_waitcnt vmcnt(21)
	v_mov_b32_e32 v87, v16
	v_mov_b32_e32 v16, v5
	v_mov_b32_e32 v84, v6
	s_waitcnt vmcnt(17)
	v_cndmask_b32_e64 v62, 0, v135, s[2:3]
	v_cndmask_b32_e64 v56, 0, v134, s[2:3]
	v_cndmask_b32_e64 v57, 0, v133, s[2:3]
	v_cndmask_b32_e64 v58, 0, v132, s[2:3]
	s_mov_b32 s100, 0xffffbe40
	s_mov_b32 s101, -1
	v_lshl_add_u64 v[242:243], v[74:75], 0, s[100:101]
	global_load_dwordx4 v[132:135], v[242:243], off
	v_mov_b32_e32 v38, v44
	v_mov_b32_e32 v39, v28
	v_mov_b32_e32 v85, v18
	v_mov_b32_e32 v18, v7
	v_mov_b32_e32 v80, v0
	v_mov_b32_e32 v81, v12
	v_mov_b32_e32 v12, v1
	v_mov_b32_e32 v82, v2
	v_mov_b32_e32 v83, v14
	v_mov_b32_e32 v14, v3
	s_waitcnt vmcnt(17)
	v_cndmask_b32_e64 v59, 0, v136, s[4:5]
	v_cndmask_b32_e64 v63, 0, v139, s[4:5]
	v_cndmask_b32_e64 v55, 0, v137, s[4:5]
	v_lshlrev_b32_e32 v53, 16, v59
	v_lshlrev_b32_e32 v52, 16, v58
	v_pk_mul_f32 v[52:53], v[38:39], v[52:53]
	v_cndmask_b32_e64 v138, 0, v138, s[4:5]
	v_add_f32_e32 v28, v32, v52
	v_add_f32_e32 v61, v28, v53
	v_and_b32_e32 v53, 0xffff0000, v59
	v_and_b32_e32 v52, 0xffff0000, v58
	v_mov_b32_e32 v28, v45
	v_pk_mul_f32 v[44:45], v[28:29], v[52:53]
	v_lshlrev_b32_e32 v53, 16, v55
	v_add_f32_e32 v44, v33, v44
	v_add_f32_e32 v60, v44, v45
	v_lshlrev_b32_e32 v52, 16, v57
	v_mov_b32_e32 v44, v46
	v_mov_b32_e32 v45, v30
	v_pk_mul_f32 v[52:53], v[44:45], v[52:53]
	s_nop 0
	v_add_f32_e32 v30, v34, v52
	v_add_f32_e32 v59, v30, v53
	v_and_b32_e32 v53, 0xffff0000, v55
	v_and_b32_e32 v52, 0xffff0000, v57
	v_mov_b32_e32 v30, v47
	v_pk_mul_f32 v[46:47], v[30:31], v[52:53]
	v_lshlrev_b32_e32 v53, 16, v138
	v_add_f32_e32 v46, v35, v46
	v_add_f32_e32 v58, v46, v47
	v_lshlrev_b32_e32 v52, 16, v56
	v_mov_b32_e32 v46, v8
	v_mov_b32_e32 v47, v20
	v_pk_mul_f32 v[52:53], v[46:47], v[52:53]
	v_mov_b32_e32 v20, v9
	v_add_f32_e32 v8, v24, v52
	v_add_f32_e32 v55, v8, v53
	v_and_b32_e32 v53, 0xffff0000, v138
	s_mov_b32 s100, 0x40
	s_mov_b32 s101, 0
	v_lshl_add_u64 v[242:243], v[74:75], 0, s[100:101]
	global_load_dwordx4 v[136:139], v[242:243], off
	v_and_b32_e32 v52, 0xffff0000, v56
	v_pk_mul_f32 v[8:9], v[20:21], v[52:53]
	v_mov_b32_e32 v56, v10
	v_add_f32_e32 v8, v25, v8
	v_add_f32_e32 v54, v8, v9
	v_lshlrev_b32_e32 v9, 16, v63
	v_lshlrev_b32_e32 v8, 16, v62
	v_mov_b32_e32 v57, v22
	v_pk_mul_f32 v[8:9], v[56:57], v[8:9]
	v_mov_b32_e32 v22, v11
	v_add_f32_e32 v8, v26, v8
	v_add_f32_e32 v53, v8, v9
	v_and_b32_e32 v9, 0xffff0000, v63
	v_and_b32_e32 v8, 0xffff0000, v62
	v_pk_mul_f32 v[8:9], v[22:23], v[8:9]
	s_nop 0
	v_add_f32_e32 v8, v27, v8
	v_add_f32_e32 v52, v8, v9
	v_lshl_add_u64 v[8:9], v[78:79], 0, s[62:63]
	s_waitcnt vmcnt(17)
	v_cndmask_b32_e64 v62, 0, v143, s[8:9]
	v_cndmask_b32_e64 v63, 0, v142, s[8:9]
	v_cndmask_b32_e64 v64, 0, v141, s[8:9]
	v_cndmask_b32_e64 v65, 0, v140, s[8:9]
	s_mov_b32 s100, 0x35a40
	s_mov_b32 s101, 0
	v_lshl_add_u64 v[242:243], v[74:75], 0, s[100:101]
	global_load_dwordx4 v[140:143], v[242:243], off
	s_waitcnt vmcnt(17)
	v_cndmask_b32_e64 v67, 0, v162, s[10:11]
	v_cndmask_b32_e64 v66, 0, v163, s[10:11]
	v_lshlrev_b32_e32 v9, 16, v67
	v_lshlrev_b32_e32 v8, 16, v65
	v_pk_mul_f32 v[8:9], v[86:87], v[8:9]
	v_cndmask_b32_e64 v164, 0, v164, s[10:11]
	v_add_f32_e32 v4, v61, v8
	v_add_f32_e32 v61, v4, v9
	v_and_b32_e32 v9, 0xffff0000, v67
	v_and_b32_e32 v8, 0xffff0000, v65
	v_pk_mul_f32 v[4:5], v[16:17], v[8:9]
	v_cndmask_b32_e64 v165, 0, v165, s[10:11]
	v_add_f32_e32 v4, v60, v4
	v_add_f32_e32 v8, v4, v5
	v_lshlrev_b32_e32 v5, 16, v66
	v_lshlrev_b32_e32 v4, 16, v64
	v_pk_mul_f32 v[4:5], v[84:85], v[4:5]
	s_nop 0
	v_add_f32_e32 v4, v59, v4
	v_add_f32_e32 v6, v4, v5
	v_and_b32_e32 v5, 0xffff0000, v66
	v_and_b32_e32 v4, 0xffff0000, v64
	v_pk_mul_f32 v[4:5], v[18:19], v[4:5]
	s_nop 0
	v_add_f32_e32 v4, v58, v4
	v_add_f32_e32 v7, v4, v5
	v_lshlrev_b32_e32 v5, 16, v164
	v_lshlrev_b32_e32 v4, 16, v63
	v_pk_mul_f32 v[4:5], v[80:81], v[4:5]
	s_nop 0
	v_add_f32_e32 v0, v55, v4
	v_add_f32_e32 v9, v0, v5
	v_and_b32_e32 v5, 0xffff0000, v164
	v_and_b32_e32 v4, 0xffff0000, v63
	v_pk_mul_f32 v[0:1], v[12:13], v[4:5]
	s_nop 0
	v_add_f32_e32 v0, v54, v0
	v_add_f32_e32 v4, v0, v1
	v_lshlrev_b32_e32 v1, 16, v165
	v_lshlrev_b32_e32 v0, 16, v62
	v_pk_mul_f32 v[0:1], v[82:83], v[0:1]
	v_cvt_pk_bf16_f32 v2, v9, v4
	s_nop 0
	v_add_f32_e32 v0, v53, v0
	v_add_f32_e32 v5, v0, v1
	v_and_b32_e32 v1, 0xffff0000, v165
	s_mov_b32 s100, 0x39c40
	s_mov_b32 s101, 0
	v_lshl_add_u64 v[242:243], v[74:75], 0, s[100:101]
	global_load_dwordx4 v[162:165], v[242:243], off
	v_and_b32_e32 v0, 0xffff0000, v62
	v_pk_mul_f32 v[0:1], v[14:15], v[0:1]
	s_nop 0
	v_add_f32_e32 v0, v52, v0
	v_add_f32_e32 v3, v0, v1
	v_cvt_pk_bf16_f32 v0, v61, v8
	v_cvt_pk_bf16_f32 v1, v6, v7
	v_cvt_pk_bf16_f32 v3, v5, v3
	s_mov_b32 s81, 0x35000
	v_add_co_u32_e32 v68, vcc, s81, v74
	s_mov_b32 s81, 0x39000
	s_nop 0
	v_addc_co_u32_e32 v69, vcc, 0, v75, vcc
	v_add_co_u32_e32 v70, vcc, s81, v74
	s_mov_b32 s81, 0x3d000
	s_nop 0
	v_addc_co_u32_e32 v71, vcc, 0, v75, vcc
	v_add_co_u32_e32 v72, vcc, s81, v74
	s_mov_b32 s81, 0x42000
	s_nop 0
	v_addc_co_u32_e32 v73, vcc, 0, v75, vcc
	v_add_co_u32_e32 v76, vcc, s81, v74
	s_waitcnt vmcnt(17)
	v_cndmask_b32_e64 v10, 0, v169, s[12:13]
	v_cndmask_b32_e64 v11, 0, v168, s[12:13]
	v_cndmask_b32_e64 v8, 0, v167, s[12:13]
	v_cndmask_b32_e64 v9, 0, v166, s[12:13]
	s_mov_b32 s100, 0x3de40
	s_mov_b32 s101, 0
	v_lshl_add_u64 v[242:243], v[74:75], 0, s[100:101]
	global_load_dwordx4 v[166:169], v[242:243], off
	v_addc_co_u32_e32 v77, vcc, 0, v75, vcc
	s_waitcnt vmcnt(17)
	v_cndmask_b32_e64 v53, 0, v172, s[14:15]
	v_cndmask_b32_e64 v52, 0, v175, s[14:15]
	v_cndmask_b32_e64 v7, 0, v173, s[14:15]
	v_lshlrev_b32_e32 v5, 16, v53
	v_lshlrev_b32_e32 v4, 16, v9
	v_pk_mul_f32 v[4:5], v[38:39], v[4:5]
	v_cndmask_b32_e64 v174, 0, v174, s[14:15]
	v_add_f32_e32 v4, v32, v4
	v_add_f32_e32 v58, v4, v5
	v_and_b32_e32 v5, 0xffff0000, v53
	v_and_b32_e32 v4, 0xffff0000, v9
	v_pk_mul_f32 v[4:5], v[28:29], v[4:5]
	s_nop 0
	v_add_f32_e32 v4, v33, v4
	v_add_f32_e32 v59, v4, v5
	v_lshlrev_b32_e32 v5, 16, v7
	v_lshlrev_b32_e32 v4, 16, v8
	v_pk_mul_f32 v[4:5], v[44:45], v[4:5]
	s_nop 0
	v_add_f32_e32 v4, v34, v4
	v_add_f32_e32 v9, v4, v5
	v_and_b32_e32 v5, 0xffff0000, v7
	v_and_b32_e32 v4, 0xffff0000, v8
	v_pk_mul_f32 v[4:5], v[30:31], v[4:5]
	s_nop 0
	v_add_f32_e32 v4, v35, v4
	v_add_f32_e32 v8, v4, v5
	v_lshlrev_b32_e32 v5, 16, v174
	v_lshlrev_b32_e32 v4, 16, v11
	v_pk_mul_f32 v[4:5], v[46:47], v[4:5]
	s_nop 0
	v_add_f32_e32 v4, v24, v4
	v_add_f32_e32 v7, v4, v5
	v_and_b32_e32 v5, 0xffff0000, v174
	s_mov_b32 s100, 0x42040
	s_mov_b32 s101, 0
	v_lshl_add_u64 v[242:243], v[74:75], 0, s[100:101]
	global_load_dwordx4 v[172:175], v[242:243], off
	v_and_b32_e32 v4, 0xffff0000, v11
	v_pk_mul_f32 v[4:5], v[20:21], v[4:5]
	v_and_b32_e32 v11, 0xffff0000, v52
	v_add_f32_e32 v4, v25, v4
	v_add_f32_e32 v6, v4, v5
	v_lshlrev_b32_e32 v5, 16, v52
	v_lshlrev_b32_e32 v4, 16, v10
	v_pk_mul_f32 v[4:5], v[56:57], v[4:5]
	v_and_b32_e32 v10, 0xffff0000, v10
	v_add_f32_e32 v4, v26, v4
	v_pk_mul_f32 v[10:11], v[22:23], v[10:11]
	v_add_f32_e32 v5, v4, v5
	v_add_f32_e32 v4, v27, v10
	v_add_f32_e32 v4, v4, v11
	s_waitcnt vmcnt(17)
	v_cndmask_b32_e64 v60, 0, v179, s[16:17]
	v_cndmask_b32_e64 v61, 0, v178, s[16:17]
	v_cndmask_b32_e64 v62, 0, v177, s[16:17]
	v_cndmask_b32_e64 v63, 0, v176, s[16:17]
	s_mov_b32 s100, 0x77a40
	s_mov_b32 s101, 0
	v_lshl_add_u64 v[242:243], v[74:75], 0, s[100:101]
	global_load_dwordx4 v[176:179], v[242:243], off
	v_lshlrev_b32_e32 v10, 16, v63
	s_waitcnt vmcnt(17)
	v_cndmask_b32_e64 v180, 0, v180, s[10:11]
	v_lshlrev_b32_e32 v11, 16, v180
	v_pk_mul_f32 v[10:11], v[86:87], v[10:11]
	v_cndmask_b32_e64 v181, 0, v181, s[10:11]
	v_add_f32_e32 v10, v58, v10
	v_add_f32_e32 v58, v10, v11
	v_and_b32_e32 v11, 0xffff0000, v180
	v_and_b32_e32 v10, 0xffff0000, v63
	v_pk_mul_f32 v[10:11], v[16:17], v[10:11]
	v_cndmask_b32_e64 v182, 0, v182, s[10:11]
	v_add_f32_e32 v10, v59, v10
	v_add_f32_e32 v52, v10, v11
	v_lshlrev_b32_e32 v11, 16, v181
	v_lshlrev_b32_e32 v10, 16, v62
	v_pk_mul_f32 v[10:11], v[84:85], v[10:11]
	v_cndmask_b32_e64 v183, 0, v183, s[10:11]
	v_add_f32_e32 v9, v9, v10
	v_add_f32_e32 v59, v9, v11
	v_and_b32_e32 v11, 0xffff0000, v181
	v_and_b32_e32 v10, 0xffff0000, v62
	v_pk_mul_f32 v[10:11], v[18:19], v[10:11]
	v_lshlrev_b32_e32 v9, 16, v182
	v_add_f32_e32 v8, v8, v10
	v_add_f32_e32 v10, v8, v11
	v_lshlrev_b32_e32 v8, 16, v61
	v_pk_mul_f32 v[8:9], v[80:81], v[8:9]
	s_nop 0
	v_add_f32_e32 v7, v7, v8
	v_add_f32_e32 v11, v7, v9
	v_and_b32_e32 v9, 0xffff0000, v182
	v_and_b32_e32 v8, 0xffff0000, v61
	v_pk_mul_f32 v[8:9], v[12:13], v[8:9]
	v_lshlrev_b32_e32 v7, 16, v183
	v_add_f32_e32 v6, v6, v8
	v_add_f32_e32 v8, v6, v9
	v_lshlrev_b32_e32 v6, 16, v60
	v_pk_mul_f32 v[6:7], v[82:83], v[6:7]
	s_nop 0
	v_add_f32_e32 v5, v5, v6
	v_add_f32_e32 v9, v5, v7
	v_and_b32_e32 v7, 0xffff0000, v183
	s_mov_b32 s100, 0x7bc40
	s_mov_b32 s101, 0
	v_lshl_add_u64 v[242:243], v[74:75], 0, s[100:101]
	global_load_dwordx4 v[180:183], v[242:243], off
	v_and_b32_e32 v6, 0xffff0000, v60
	v_pk_mul_f32 v[6:7], v[14:15], v[6:7]
	v_cvt_pk_bf16_f32 v5, v59, v10
	s_nop 0
	v_add_f32_e32 v4, v4, v6
	v_add_f32_e32 v7, v4, v7
	v_cvt_pk_bf16_f32 v4, v58, v52
	v_cvt_pk_bf16_f32 v6, v11, v8
	v_cvt_pk_bf16_f32 v7, v9, v7
	s_mov_b32 s81, 0x77000
	v_add_co_u32_e32 v60, vcc, s81, v74
	s_mov_b32 s81, 0x7b000
	s_nop 0
	v_addc_co_u32_e32 v61, vcc, 0, v75, vcc
	v_add_co_u32_e32 v62, vcc, s81, v74
	s_mov_b32 s81, 0x7f000
	s_nop 0
	v_addc_co_u32_e32 v63, vcc, 0, v75, vcc
	v_add_co_u32_e32 v64, vcc, s81, v74
	s_mov_b32 s81, 0x84000
	s_nop 0
	v_addc_co_u32_e32 v65, vcc, 0, v75, vcc
	v_add_co_u32_e32 v66, vcc, s81, v74
	s_waitcnt vmcnt(17)
	v_cndmask_b32_e64 v54, 0, v187, s[18:19]
	v_cndmask_b32_e64 v55, 0, v186, s[18:19]
	v_cndmask_b32_e64 v52, 0, v185, s[18:19]
	v_cndmask_b32_e64 v53, 0, v184, s[18:19]
	s_mov_b32 s100, 0x7fe40
	s_mov_b32 s101, 0
	v_lshl_add_u64 v[242:243], v[74:75], 0, s[100:101]
	global_load_dwordx4 v[184:187], v[242:243], off
	v_addc_co_u32_e32 v67, vcc, 0, v75, vcc
	s_waitcnt vmcnt(17)
	v_cndmask_b32_e64 v123, 0, v194, s[22:23]
	v_cndmask_b32_e64 v124, 0, v193, s[22:23]
	v_cndmask_b32_e64 v125, 0, v192, s[22:23]
	s_waitcnt vmcnt(16)
	v_cndmask_b32_e64 v59, 0, v212, s[20:21]
	v_cndmask_b32_e64 v58, 0, v215, s[20:21]
	v_cndmask_b32_e64 v11, 0, v213, s[20:21]
	v_lshlrev_b32_e32 v9, 16, v59
	v_lshlrev_b32_e32 v8, 16, v53
	v_pk_mul_f32 v[8:9], v[38:39], v[8:9]
	v_cndmask_b32_e64 v214, 0, v214, s[20:21]
	v_add_f32_e32 v8, v32, v8
	v_add_f32_e32 v122, v8, v9
	v_and_b32_e32 v9, 0xffff0000, v59
	v_and_b32_e32 v8, 0xffff0000, v53
	v_pk_mul_f32 v[8:9], v[28:29], v[8:9]
	s_nop 0
	v_add_f32_e32 v8, v33, v8
	v_add_f32_e32 v59, v8, v9
	v_lshlrev_b32_e32 v9, 16, v11
	v_lshlrev_b32_e32 v8, 16, v52
	v_pk_mul_f32 v[8:9], v[44:45], v[8:9]
	s_nop 0
	v_add_f32_e32 v8, v34, v8
	v_add_f32_e32 v53, v8, v9
	v_and_b32_e32 v9, 0xffff0000, v11
	v_and_b32_e32 v8, 0xffff0000, v52
	v_pk_mul_f32 v[8:9], v[30:31], v[8:9]
	s_nop 0
	v_add_f32_e32 v8, v35, v8
	v_add_f32_e32 v52, v8, v9
	v_lshlrev_b32_e32 v9, 16, v214
	v_lshlrev_b32_e32 v8, 16, v55
	v_pk_mul_f32 v[8:9], v[46:47], v[8:9]
	s_nop 0
	v_add_f32_e32 v8, v24, v8
	v_add_f32_e32 v11, v8, v9
	v_and_b32_e32 v9, 0xffff0000, v214
	v_and_b32_e32 v8, 0xffff0000, v55
	v_pk_mul_f32 v[8:9], v[20:21], v[8:9]
	v_and_b32_e32 v55, 0xffff0000, v58
	v_add_f32_e32 v8, v25, v8
	v_add_f32_e32 v10, v8, v9
	v_lshlrev_b32_e32 v9, 16, v58
	v_cndmask_b32_e64 v58, 0, v195, s[22:23]
	s_mov_b32 s100, 0x84040
	s_mov_b32 s101, 0
	v_lshl_add_u64 v[242:243], v[74:75], 0, s[100:101]
	global_load_dwordx4 v[192:195], v[242:243], off
	s_mov_b32 s100, 0xb9a40
	s_mov_b32 s101, 0
	v_lshl_add_u64 v[242:243], v[74:75], 0, s[100:101]
	global_load_dwordx4 v[212:215], v[242:243], off
	v_lshlrev_b32_e32 v8, 16, v54
	v_pk_mul_f32 v[8:9], v[56:57], v[8:9]
	v_and_b32_e32 v54, 0xffff0000, v54
	v_add_f32_e32 v8, v26, v8
	v_pk_mul_f32 v[54:55], v[22:23], v[54:55]
	v_add_f32_e32 v9, v8, v9
	v_add_f32_e32 v8, v27, v54
	v_add_f32_e32 v8, v8, v55
	v_lshlrev_b32_e32 v54, 16, v125
	s_waitcnt vmcnt(17)
	v_cndmask_b32_e64 v216, 0, v216, s[10:11]
	v_lshlrev_b32_e32 v55, 16, v216
	v_pk_mul_f32 v[54:55], v[86:87], v[54:55]
	v_cndmask_b32_e64 v217, 0, v217, s[10:11]
	v_add_f32_e32 v54, v122, v54
	v_add_f32_e32 v122, v54, v55
	v_and_b32_e32 v55, 0xffff0000, v216
	v_and_b32_e32 v54, 0xffff0000, v125
	v_pk_mul_f32 v[54:55], v[16:17], v[54:55]
	v_cndmask_b32_e64 v218, 0, v218, s[10:11]
	v_add_f32_e32 v54, v59, v54
	v_add_f32_e32 v59, v54, v55
	v_lshlrev_b32_e32 v55, 16, v217
	v_lshlrev_b32_e32 v54, 16, v124
	v_pk_mul_f32 v[54:55], v[84:85], v[54:55]
	v_cndmask_b32_e64 v219, 0, v219, s[10:11]
	v_add_f32_e32 v53, v53, v54
	v_add_f32_e32 v118, v53, v55
	v_and_b32_e32 v55, 0xffff0000, v217
	v_and_b32_e32 v54, 0xffff0000, v124
	v_pk_mul_f32 v[54:55], v[18:19], v[54:55]
	v_lshlrev_b32_e32 v53, 16, v218
	v_add_f32_e32 v52, v52, v54
	v_add_f32_e32 v54, v52, v55
	v_lshlrev_b32_e32 v52, 16, v123
	v_pk_mul_f32 v[52:53], v[80:81], v[52:53]
	s_nop 0
	v_add_f32_e32 v11, v11, v52
	v_add_f32_e32 v55, v11, v53
	v_and_b32_e32 v53, 0xffff0000, v218
	v_and_b32_e32 v52, 0xffff0000, v123
	v_pk_mul_f32 v[52:53], v[12:13], v[52:53]
	v_lshlrev_b32_e32 v11, 16, v219
	v_add_f32_e32 v10, v10, v52
	v_add_f32_e32 v52, v10, v53
	v_lshlrev_b32_e32 v10, 16, v58
	v_pk_mul_f32 v[10:11], v[82:83], v[10:11]
	s_nop 0
	v_add_f32_e32 v9, v9, v10
	v_add_f32_e32 v53, v9, v11
	v_and_b32_e32 v11, 0xffff0000, v219
	s_mov_b32 s100, 0xbdc40
	s_mov_b32 s101, 0
	v_lshl_add_u64 v[242:243], v[74:75], 0, s[100:101]
	global_load_dwordx4 v[216:219], v[242:243], off
	v_and_b32_e32 v10, 0xffff0000, v58
	v_pk_mul_f32 v[10:11], v[14:15], v[10:11]
	v_cvt_pk_bf16_f32 v9, v118, v54
	s_nop 0
	v_add_f32_e32 v8, v8, v10
	v_add_f32_e32 v11, v8, v11
	v_cvt_pk_bf16_f32 v8, v122, v59
	v_cvt_pk_bf16_f32 v10, v55, v52
	v_cvt_pk_bf16_f32 v11, v53, v11
	s_mov_b32 s81, 0xb9000
	v_add_co_u32_e32 v52, vcc, s81, v74
	s_mov_b32 s81, 0xbd000
	s_nop 0
	v_addc_co_u32_e32 v53, vcc, 0, v75, vcc
	v_add_co_u32_e32 v54, vcc, s81, v74
	s_mov_b32 s81, 0xc1000
	s_nop 0
	v_addc_co_u32_e32 v55, vcc, 0, v75, vcc
	s_waitcnt vmcnt(17)
	v_cndmask_b32_e64 v122, 0, v223, s[0:1]
	v_cndmask_b32_e64 v123, 0, v222, s[0:1]
	v_cndmask_b32_e64 v124, 0, v221, s[0:1]
	v_cndmask_b32_e64 v125, 0, v220, s[0:1]
	s_mov_b32 s100, 0xc1e40
	s_mov_b32 s101, 0
	v_lshl_add_u64 v[242:243], v[74:75], 0, s[100:101]
	global_load_dwordx4 v[220:223], v[242:243], off
	v_lshlrev_b32_e32 v58, 16, v125
	s_waitcnt vmcnt(17)
	v_cndmask_b32_e64 v224, 0, v224, s[24:25]
	v_lshlrev_b32_e32 v59, 16, v224
	v_pk_mul_f32 v[38:39], v[38:39], v[58:59]
	v_cndmask_b32_e64 v225, 0, v225, s[24:25]
	v_add_f32_e32 v32, v32, v38
	v_add_f32_e32 v126, v32, v39
	v_and_b32_e32 v39, 0xffff0000, v224
	v_and_b32_e32 v38, 0xffff0000, v125
	v_pk_mul_f32 v[28:29], v[28:29], v[38:39]
	v_cndmask_b32_e64 v226, 0, v226, s[24:25]
	v_add_f32_e32 v28, v33, v28
	v_add_f32_e32 v33, v28, v29
	v_lshlrev_b32_e32 v29, 16, v225
	v_lshlrev_b32_e32 v28, 16, v124
	v_pk_mul_f32 v[28:29], v[44:45], v[28:29]
	v_cndmask_b32_e64 v227, 0, v227, s[24:25]
	v_add_f32_e32 v28, v34, v28
	v_add_f32_e32 v32, v28, v29
	v_and_b32_e32 v29, 0xffff0000, v225
	v_and_b32_e32 v28, 0xffff0000, v124
	v_pk_mul_f32 v[28:29], v[30:31], v[28:29]
	v_lshlrev_b32_e32 v31, 16, v226
	v_lshlrev_b32_e32 v30, 16, v123
	v_pk_mul_f32 v[30:31], v[46:47], v[30:31]
	v_add_f32_e32 v28, v35, v28
	v_add_f32_e32 v24, v24, v30
	v_add_f32_e32 v29, v28, v29
	v_add_f32_e32 v28, v24, v31
	v_and_b32_e32 v31, 0xffff0000, v226
	v_and_b32_e32 v30, 0xffff0000, v123
	v_pk_mul_f32 v[20:21], v[20:21], v[30:31]
	v_and_b32_e32 v31, 0xffff0000, v227
	v_add_f32_e32 v20, v25, v20
	v_add_f32_e32 v24, v20, v21
	v_lshlrev_b32_e32 v21, 16, v227
	s_mov_b32 s100, 0xc6040
	s_mov_b32 s101, 0
	v_lshl_add_u64 v[242:243], v[74:75], 0, s[100:101]
	global_load_dwordx4 v[224:227], v[242:243], off
	v_lshlrev_b32_e32 v20, 16, v122
	v_pk_mul_f32 v[20:21], v[56:57], v[20:21]
	v_add_co_u32_e32 v56, vcc, s81, v74
	s_mov_b32 s81, 0xc6000
	s_nop 0
	v_addc_co_u32_e32 v57, vcc, 0, v75, vcc
	v_and_b32_e32 v30, 0xffff0000, v122
	v_add_co_u32_e32 v58, vcc, s81, v74
	v_add_f32_e32 v20, v26, v20
	v_pk_mul_f32 v[22:23], v[22:23], v[30:31]
	v_addc_co_u32_e32 v59, vcc, 0, v75, vcc
	v_add_f32_e32 v21, v20, v21
	v_add_f32_e32 v20, v27, v22
	v_add_f32_e32 v20, v20, v23
	s_waitcnt vmcnt(17)
	v_cndmask_b32_e64 v25, 0, v231, s[26:27]
	v_cndmask_b32_e64 v26, 0, v230, s[26:27]
	v_cndmask_b32_e64 v27, 0, v229, s[26:27]
	v_cndmask_b32_e64 v30, 0, v228, s[26:27]
	v_lshlrev_b32_e32 v22, 16, v30
	s_waitcnt vmcnt(16)
	v_cndmask_b32_e64 v38, 0, v232, s[10:11]
	v_lshlrev_b32_e32 v23, 16, v38
	v_pk_mul_f32 v[22:23], v[86:87], v[22:23]
	v_cndmask_b32_e64 v35, 0, v233, s[10:11]
	v_add_f32_e32 v22, v126, v22
	v_add_f32_e32 v39, v22, v23
	v_and_b32_e32 v23, 0xffff0000, v38
	v_and_b32_e32 v22, 0xffff0000, v30
	v_pk_mul_f32 v[16:17], v[16:17], v[22:23]
	v_cndmask_b32_e64 v34, 0, v234, s[10:11]
	v_add_f32_e32 v16, v33, v16
	v_add_f32_e32 v22, v16, v17
	v_lshlrev_b32_e32 v17, 16, v35
	v_lshlrev_b32_e32 v16, 16, v27
	v_pk_mul_f32 v[16:17], v[84:85], v[16:17]
	v_cndmask_b32_e64 v31, 0, v235, s[10:11]
	v_add_f32_e32 v16, v32, v16
	v_add_f32_e32 v23, v16, v17
	v_and_b32_e32 v17, 0xffff0000, v35
	v_and_b32_e32 v16, 0xffff0000, v27
	v_pk_mul_f32 v[16:17], v[18:19], v[16:17]
	s_nop 0
	v_add_f32_e32 v16, v29, v16
	v_add_f32_e32 v18, v16, v17
	v_lshlrev_b32_e32 v17, 16, v34
	v_lshlrev_b32_e32 v16, 16, v26
	v_pk_mul_f32 v[16:17], v[80:81], v[16:17]
	s_nop 0
	v_add_f32_e32 v16, v28, v16
	v_add_f32_e32 v19, v16, v17
	v_and_b32_e32 v17, 0xffff0000, v34
	v_and_b32_e32 v16, 0xffff0000, v26
	v_pk_mul_f32 v[12:13], v[12:13], v[16:17]
	s_nop 0
	v_add_f32_e32 v12, v24, v12
	v_add_f32_e32 v16, v12, v13
	v_lshlrev_b32_e32 v13, 16, v31
	v_lshlrev_b32_e32 v12, 16, v25
	v_pk_mul_f32 v[12:13], v[82:83], v[12:13]
	s_nop 0
	v_add_f32_e32 v12, v21, v12
	v_add_f32_e32 v17, v12, v13
	v_and_b32_e32 v13, 0xffff0000, v31
	v_and_b32_e32 v12, 0xffff0000, v25
	v_pk_mul_f32 v[12:13], v[14:15], v[12:13]
	v_cvt_pk_bf16_f32 v14, v19, v16
	s_nop 0
	v_add_f32_e32 v12, v20, v12
	v_add_f32_e32 v15, v12, v13
	v_cvt_pk_bf16_f32 v12, v39, v22
	v_cvt_pk_bf16_f32 v13, v23, v18
	v_cvt_pk_bf16_f32 v15, v17, v15
	global_load_dwordx4 v[24:27], v144, s[84:85] offset:144
	global_load_dwordx4 v[80:83], v144, s[84:85] offset:128
	s_mov_b64 s[84:85], 0x1080
	v_lshl_add_u64 v[16:17], v[40:41], 0, s[84:85]
	s_mov_b64 s[84:85], 0x2080
	global_load_dwordx4 v[44:47], v[36:37], off offset:128
	s_nop 0
	global_load_dwordx4 v[36:39], v[16:17], off offset:16
	v_lshl_add_u64 v[16:17], v[40:41], 0, s[84:85]
	s_mov_b64 s[84:85], 0x3080
	v_lshl_add_u64 v[120:121], v[78:79], 0, 64
	v_lshl_add_u64 v[28:29], v[40:41], 0, s[84:85]
	v_lshl_add_u64 v[78:79], v[120:121], 0, s[58:59]
	global_load_dwordx4 v[20:23], v[42:43], off offset:128
	s_nop 0
	global_load_dwordx4 v[16:19], v[16:17], off offset:16
	s_nop 0
	global_load_dwordx4 v[32:35], v[48:49], off offset:128
	s_nop 0
	global_load_dwordx4 v[28:31], v[28:29], off offset:16
	s_nop 0
	global_load_dwordx4 v[40:43], v[50:51], off offset:144
	s_nop 0
	global_load_dwordx4 v[48:51], v[50:51], off offset:128
	s_ashr_i32 s81, s80, 31
	v_lshl_add_u64 v[78:79], v[120:121], 0, s[60:61]
	s_waitcnt vmcnt(25)
	v_cndmask_b32_e64 v122, 0, v239, s[2:3]
	v_cndmask_b32_e64 v123, 0, v238, s[2:3]
	v_cndmask_b32_e64 v124, 0, v237, s[2:3]
	v_cndmask_b32_e64 v118, 0, v236, s[2:3]
	s_waitcnt vmcnt(8)
	v_mov_b32_e32 v78, v80
	s_waitcnt vmcnt(7)
	v_mov_b32_e32 v79, v44
	v_cndmask_b32_e64 v126, 0, v249, s[4:5]
	v_cndmask_b32_e64 v87, 0, v246, s[4:5]
	v_cndmask_b32_e64 v127, 0, v248, s[4:5]
	v_cndmask_b32_e64 v86, 0, v247, s[4:5]
	v_lshlrev_b32_e32 v85, 16, v87
	v_lshlrev_b32_e32 v84, 16, v118
	v_pk_mul_f32 v[84:85], v[78:79], v[84:85]
	s_nop 0
	s_waitcnt vmcnt(0)
	v_add_f32_e32 v44, v48, v84
	v_add_f32_e32 v119, v44, v85
	v_and_b32_e32 v85, 0xffff0000, v87
	v_and_b32_e32 v84, 0xffff0000, v118
	v_mov_b32_e32 v44, v81
	v_pk_mul_f32 v[80:81], v[44:45], v[84:85]
	v_lshlrev_b32_e32 v85, 16, v86
	v_add_f32_e32 v80, v49, v80
	v_add_f32_e32 v118, v80, v81
	v_lshlrev_b32_e32 v84, 16, v124
	v_mov_b32_e32 v80, v82
	v_mov_b32_e32 v81, v46
	v_pk_mul_f32 v[84:85], v[80:81], v[84:85]
	s_nop 0
	v_add_f32_e32 v46, v50, v84
	v_add_f32_e32 v87, v46, v85
	v_and_b32_e32 v85, 0xffff0000, v86
	v_and_b32_e32 v84, 0xffff0000, v124
	v_mov_b32_e32 v46, v83
	v_pk_mul_f32 v[82:83], v[46:47], v[84:85]
	v_lshlrev_b32_e32 v85, 16, v127
	v_add_f32_e32 v82, v51, v82
	v_add_f32_e32 v86, v82, v83
	v_lshlrev_b32_e32 v84, 16, v123
	v_mov_b32_e32 v82, v24
	v_mov_b32_e32 v83, v36
	v_pk_mul_f32 v[84:85], v[82:83], v[84:85]
	v_mov_b32_e32 v36, v25
	v_add_f32_e32 v24, v40, v84
	v_add_f32_e32 v125, v24, v85
	v_and_b32_e32 v85, 0xffff0000, v127
	v_and_b32_e32 v84, 0xffff0000, v123
	v_pk_mul_f32 v[24:25], v[36:37], v[84:85]
	v_mov_b32_e32 v84, v26
	v_add_f32_e32 v24, v41, v24
	v_add_f32_e32 v124, v24, v25
	v_lshlrev_b32_e32 v25, 16, v126
	v_lshlrev_b32_e32 v24, 16, v122
	v_mov_b32_e32 v85, v38
	v_pk_mul_f32 v[24:25], v[84:85], v[24:25]
	v_mov_b32_e32 v38, v27
	v_add_f32_e32 v24, v42, v24
	v_add_f32_e32 v123, v24, v25
	v_and_b32_e32 v25, 0xffff0000, v126
	v_and_b32_e32 v24, 0xffff0000, v122
	v_pk_mul_f32 v[24:25], v[38:39], v[24:25]
	s_nop 0
	v_add_f32_e32 v24, v43, v24
	v_add_f32_e32 v122, v24, v25
	v_lshl_add_u64 v[24:25], v[120:121], 0, s[62:63]
	v_mov_b32_e32 v120, v20
	v_mov_b32_e32 v121, v32
	v_mov_b32_e32 v32, v21
	v_cndmask_b32_e64 v126, 0, v135, s[8:9]
	v_cndmask_b32_e64 v127, 0, v134, s[8:9]
	v_cndmask_b32_e64 v128, 0, v133, s[8:9]
	v_cndmask_b32_e64 v129, 0, v132, s[8:9]
	v_cndmask_b32_e64 v75, 0, v136, s[10:11]
	v_cndmask_b32_e64 v74, 0, v137, s[10:11]
	v_lshlrev_b32_e32 v25, 16, v75
	v_lshlrev_b32_e32 v24, 16, v129
	v_pk_mul_f32 v[24:25], v[120:121], v[24:25]
	v_cndmask_b32_e64 v138, 0, v138, s[10:11]
	v_add_f32_e32 v20, v119, v24
	v_add_f32_e32 v130, v20, v25
	v_and_b32_e32 v25, 0xffff0000, v75
	v_and_b32_e32 v24, 0xffff0000, v129
	v_pk_mul_f32 v[20:21], v[32:33], v[24:25]
	v_mov_b32_e32 v119, v34
	v_add_f32_e32 v20, v118, v20
	v_add_f32_e32 v24, v20, v21
	v_lshlrev_b32_e32 v21, 16, v74
	v_lshlrev_b32_e32 v20, 16, v128
	v_mov_b32_e32 v118, v22
	v_pk_mul_f32 v[20:21], v[118:119], v[20:21]
	v_mov_b32_e32 v34, v23
	v_add_f32_e32 v20, v87, v20
	v_add_f32_e32 v22, v20, v21
	v_and_b32_e32 v21, 0xffff0000, v74
	v_and_b32_e32 v20, 0xffff0000, v128
	v_pk_mul_f32 v[20:21], v[34:35], v[20:21]
	v_mov_b32_e32 v87, v28
	v_add_f32_e32 v20, v86, v20
	v_add_f32_e32 v23, v20, v21
	v_lshlrev_b32_e32 v21, 16, v138
	v_lshlrev_b32_e32 v20, 16, v127
	v_mov_b32_e32 v86, v16
	v_pk_mul_f32 v[20:21], v[86:87], v[20:21]
	v_mov_b32_e32 v28, v17
	v_add_f32_e32 v16, v125, v20
	v_add_f32_e32 v25, v16, v21
	v_and_b32_e32 v21, 0xffff0000, v138
	v_and_b32_e32 v20, 0xffff0000, v127
	v_pk_mul_f32 v[16:17], v[28:29], v[20:21]
	v_cndmask_b32_e64 v139, 0, v139, s[10:11]
	v_add_f32_e32 v16, v124, v16
	v_add_f32_e32 v20, v16, v17
	v_lshlrev_b32_e32 v17, 16, v139
	v_lshlrev_b32_e32 v16, 16, v126
	v_mov_b32_e32 v74, v18
	v_mov_b32_e32 v75, v30
	v_pk_mul_f32 v[16:17], v[74:75], v[16:17]
	v_mov_b32_e32 v30, v19
	v_add_f32_e32 v16, v123, v16
	v_add_f32_e32 v21, v16, v17
	v_and_b32_e32 v17, 0xffff0000, v139
	v_and_b32_e32 v16, 0xffff0000, v126
	v_pk_mul_f32 v[16:17], v[30:31], v[16:17]
	v_cvt_pk_bf16_f32 v18, v25, v20
	s_nop 0
	v_add_f32_e32 v16, v122, v16
	v_add_f32_e32 v19, v16, v17
	v_cvt_pk_bf16_f32 v16, v130, v24
	v_cvt_pk_bf16_f32 v17, v22, v23
	v_cvt_pk_bf16_f32 v19, v21, v19
	v_cndmask_b32_e64 v24, 0, v143, s[12:13]
	v_cndmask_b32_e64 v25, 0, v142, s[12:13]
	v_cndmask_b32_e64 v26, 0, v141, s[12:13]
	v_cndmask_b32_e64 v27, 0, v140, s[12:13]
	v_cndmask_b32_e64 v69, 0, v162, s[14:15]
	v_cndmask_b32_e64 v68, 0, v163, s[14:15]
	v_lshlrev_b32_e32 v21, 16, v69
	v_lshlrev_b32_e32 v20, 16, v27
	v_pk_mul_f32 v[20:21], v[78:79], v[20:21]
	v_cndmask_b32_e64 v164, 0, v164, s[14:15]
	v_add_f32_e32 v20, v48, v20
	v_add_f32_e32 v70, v20, v21
	v_and_b32_e32 v21, 0xffff0000, v69
	v_and_b32_e32 v20, 0xffff0000, v27
	v_pk_mul_f32 v[20:21], v[44:45], v[20:21]
	v_cndmask_b32_e64 v165, 0, v165, s[14:15]
	v_add_f32_e32 v20, v49, v20
	v_add_f32_e32 v69, v20, v21
	v_lshlrev_b32_e32 v21, 16, v68
	v_lshlrev_b32_e32 v20, 16, v26
	v_pk_mul_f32 v[20:21], v[80:81], v[20:21]
	s_nop 0
	v_add_f32_e32 v20, v50, v20
	v_add_f32_e32 v71, v20, v21
	v_and_b32_e32 v21, 0xffff0000, v68
	v_and_b32_e32 v20, 0xffff0000, v26
	v_pk_mul_f32 v[20:21], v[46:47], v[20:21]
	s_nop 0
	v_add_f32_e32 v20, v51, v20
	v_add_f32_e32 v68, v20, v21
	v_lshlrev_b32_e32 v21, 16, v164
	v_lshlrev_b32_e32 v20, 16, v25
	v_pk_mul_f32 v[20:21], v[82:83], v[20:21]
	s_nop 0
	v_add_f32_e32 v20, v40, v20
	v_add_f32_e32 v122, v20, v21
	v_and_b32_e32 v21, 0xffff0000, v164
	v_and_b32_e32 v20, 0xffff0000, v25
	v_pk_mul_f32 v[20:21], v[36:37], v[20:21]
	v_and_b32_e32 v25, 0xffff0000, v165
	v_add_f32_e32 v20, v41, v20
	v_add_f32_e32 v22, v20, v21
	v_lshlrev_b32_e32 v21, 16, v165
	v_lshlrev_b32_e32 v20, 16, v24
	v_pk_mul_f32 v[20:21], v[84:85], v[20:21]
	v_and_b32_e32 v24, 0xffff0000, v24
	v_add_f32_e32 v20, v42, v20
	v_pk_mul_f32 v[24:25], v[38:39], v[24:25]
	v_add_f32_e32 v21, v20, v21
	v_add_f32_e32 v20, v43, v24
	v_add_f32_e32 v20, v20, v25
	v_cndmask_b32_e64 v72, 0, v169, s[16:17]
	v_cndmask_b32_e64 v23, 0, v168, s[16:17]
	v_cndmask_b32_e64 v73, 0, v167, s[16:17]
	v_cndmask_b32_e64 v123, 0, v166, s[16:17]
	v_cndmask_b32_e64 v77, 0, v172, s[10:11]
	v_cndmask_b32_e64 v76, 0, v173, s[10:11]
	v_lshlrev_b32_e32 v25, 16, v77
	v_lshlrev_b32_e32 v24, 16, v123
	v_pk_mul_f32 v[24:25], v[120:121], v[24:25]
	v_cndmask_b32_e64 v174, 0, v174, s[10:11]
	v_add_f32_e32 v24, v70, v24
	v_add_f32_e32 v70, v24, v25
	v_and_b32_e32 v25, 0xffff0000, v77
	v_and_b32_e32 v24, 0xffff0000, v123
	v_pk_mul_f32 v[24:25], v[32:33], v[24:25]
	v_cndmask_b32_e64 v175, 0, v175, s[10:11]
	v_add_f32_e32 v24, v69, v24
	v_add_f32_e32 v69, v24, v25
	v_lshlrev_b32_e32 v25, 16, v76
	v_lshlrev_b32_e32 v24, 16, v73
	v_pk_mul_f32 v[24:25], v[118:119], v[24:25]
	s_nop 0
	v_add_f32_e32 v24, v71, v24
	v_add_f32_e32 v71, v24, v25
	v_and_b32_e32 v25, 0xffff0000, v76
	v_and_b32_e32 v24, 0xffff0000, v73
	v_pk_mul_f32 v[24:25], v[34:35], v[24:25]
	s_nop 0
	v_add_f32_e32 v24, v68, v24
	v_add_f32_e32 v68, v24, v25
	v_lshlrev_b32_e32 v25, 16, v174
	v_lshlrev_b32_e32 v24, 16, v23
	v_pk_mul_f32 v[24:25], v[86:87], v[24:25]
	s_nop 0
	v_add_f32_e32 v24, v122, v24
	v_add_f32_e32 v73, v24, v25
	v_and_b32_e32 v25, 0xffff0000, v174
	v_and_b32_e32 v24, 0xffff0000, v23
	v_pk_mul_f32 v[24:25], v[28:29], v[24:25]
	v_lshlrev_b32_e32 v23, 16, v175
	v_add_f32_e32 v22, v22, v24
	v_add_f32_e32 v24, v22, v25
	v_lshlrev_b32_e32 v22, 16, v72
	v_pk_mul_f32 v[22:23], v[74:75], v[22:23]
	s_nop 0
	v_add_f32_e32 v21, v21, v22
	v_add_f32_e32 v25, v21, v23
	v_and_b32_e32 v23, 0xffff0000, v175
	v_and_b32_e32 v22, 0xffff0000, v72
	v_pk_mul_f32 v[22:23], v[30:31], v[22:23]
	v_cvt_pk_bf16_f32 v21, v71, v68
	s_nop 0
	v_add_f32_e32 v20, v20, v22
	v_add_f32_e32 v23, v20, v23
	v_cvt_pk_bf16_f32 v20, v70, v69
	v_cvt_pk_bf16_f32 v22, v73, v24
	v_cvt_pk_bf16_f32 v23, v25, v23
	v_cndmask_b32_e64 v60, 0, v179, s[18:19]
	v_cndmask_b32_e64 v61, 0, v178, s[18:19]
	v_cndmask_b32_e64 v68, 0, v177, s[18:19]
	v_cndmask_b32_e64 v69, 0, v176, s[18:19]
	v_cndmask_b32_e64 v63, 0, v180, s[20:21]
	v_cndmask_b32_e64 v62, 0, v181, s[20:21]
	v_lshlrev_b32_e32 v25, 16, v63
	v_lshlrev_b32_e32 v24, 16, v69
	v_pk_mul_f32 v[24:25], v[78:79], v[24:25]
	v_cndmask_b32_e64 v182, 0, v182, s[20:21]
	v_add_f32_e32 v24, v48, v24
	v_add_f32_e32 v70, v24, v25
	v_and_b32_e32 v25, 0xffff0000, v63
	v_and_b32_e32 v24, 0xffff0000, v69
	v_pk_mul_f32 v[24:25], v[44:45], v[24:25]
	v_cndmask_b32_e64 v183, 0, v183, s[20:21]
	v_add_f32_e32 v24, v49, v24
	v_add_f32_e32 v69, v24, v25
	v_lshlrev_b32_e32 v25, 16, v62
	v_lshlrev_b32_e32 v24, 16, v68
	v_pk_mul_f32 v[24:25], v[80:81], v[24:25]
	s_nop 0
	v_add_f32_e32 v24, v50, v24
	v_add_f32_e32 v71, v24, v25
	v_and_b32_e32 v25, 0xffff0000, v62
	v_and_b32_e32 v24, 0xffff0000, v68
	v_pk_mul_f32 v[24:25], v[46:47], v[24:25]
	s_nop 0
	v_add_f32_e32 v24, v51, v24
	v_add_f32_e32 v68, v24, v25
	v_lshlrev_b32_e32 v25, 16, v182
	v_lshlrev_b32_e32 v24, 16, v61
	v_pk_mul_f32 v[24:25], v[82:83], v[24:25]
	s_nop 0
	v_add_f32_e32 v24, v40, v24
	v_add_f32_e32 v72, v24, v25
	v_and_b32_e32 v25, 0xffff0000, v182
	v_and_b32_e32 v24, 0xffff0000, v61
	v_pk_mul_f32 v[24:25], v[36:37], v[24:25]
	v_and_b32_e32 v61, 0xffff0000, v183
	v_add_f32_e32 v24, v41, v24
	v_add_f32_e32 v26, v24, v25
	v_lshlrev_b32_e32 v25, 16, v183
	v_lshlrev_b32_e32 v24, 16, v60
	v_pk_mul_f32 v[24:25], v[84:85], v[24:25]
	v_and_b32_e32 v60, 0xffff0000, v60
	v_add_f32_e32 v24, v42, v24
	v_pk_mul_f32 v[60:61], v[38:39], v[60:61]
	v_add_f32_e32 v25, v24, v25
	v_add_f32_e32 v24, v43, v60
	v_add_f32_e32 v24, v24, v61
	v_cndmask_b32_e64 v64, 0, v187, s[22:23]
	v_cndmask_b32_e64 v27, 0, v186, s[22:23]
	v_cndmask_b32_e64 v65, 0, v185, s[22:23]
	v_cndmask_b32_e64 v73, 0, v184, s[22:23]
	v_cndmask_b32_e64 v67, 0, v192, s[10:11]
	v_cndmask_b32_e64 v66, 0, v193, s[10:11]
	v_lshlrev_b32_e32 v61, 16, v67
	v_lshlrev_b32_e32 v60, 16, v73
	v_pk_mul_f32 v[60:61], v[120:121], v[60:61]
	v_cndmask_b32_e64 v194, 0, v194, s[10:11]
	v_add_f32_e32 v60, v70, v60
	v_add_f32_e32 v70, v60, v61
	v_and_b32_e32 v61, 0xffff0000, v67
	v_and_b32_e32 v60, 0xffff0000, v73
	v_pk_mul_f32 v[60:61], v[32:33], v[60:61]
	v_cndmask_b32_e64 v195, 0, v195, s[10:11]
	v_add_f32_e32 v60, v69, v60
	v_add_f32_e32 v67, v60, v61
	v_lshlrev_b32_e32 v61, 16, v66
	v_lshlrev_b32_e32 v60, 16, v65
	v_pk_mul_f32 v[60:61], v[118:119], v[60:61]
	s_nop 0
	v_add_f32_e32 v60, v71, v60
	v_add_f32_e32 v69, v60, v61
	v_and_b32_e32 v61, 0xffff0000, v66
	v_and_b32_e32 v60, 0xffff0000, v65
	v_pk_mul_f32 v[60:61], v[34:35], v[60:61]
	s_nop 0
	v_add_f32_e32 v60, v68, v60
	v_add_f32_e32 v65, v60, v61
	v_lshlrev_b32_e32 v61, 16, v194
	v_lshlrev_b32_e32 v60, 16, v27
	v_pk_mul_f32 v[60:61], v[86:87], v[60:61]
	s_nop 0
	v_add_f32_e32 v60, v72, v60
	v_add_f32_e32 v66, v60, v61
	v_and_b32_e32 v61, 0xffff0000, v194
	v_and_b32_e32 v60, 0xffff0000, v27
	v_pk_mul_f32 v[60:61], v[28:29], v[60:61]
	v_lshlrev_b32_e32 v27, 16, v195
	v_add_f32_e32 v26, v26, v60
	v_add_f32_e32 v60, v26, v61
	v_lshlrev_b32_e32 v26, 16, v64
	v_pk_mul_f32 v[26:27], v[74:75], v[26:27]
	s_nop 0
	v_add_f32_e32 v25, v25, v26
	v_add_f32_e32 v61, v25, v27
	v_and_b32_e32 v27, 0xffff0000, v195
	v_and_b32_e32 v26, 0xffff0000, v64
	v_pk_mul_f32 v[26:27], v[30:31], v[26:27]
	v_cvt_pk_bf16_f32 v25, v69, v65
	s_nop 0
	v_add_f32_e32 v24, v24, v26
	v_add_f32_e32 v27, v24, v27
	v_cvt_pk_bf16_f32 v24, v70, v67
	v_cvt_pk_bf16_f32 v26, v66, v60
	v_cvt_pk_bf16_f32 v27, v61, v27
	v_cndmask_b32_e64 v212, 0, v212, s[0:1]
	v_cndmask_b32_e64 v213, 0, v213, s[0:1]
	v_cndmask_b32_e64 v214, 0, v214, s[0:1]
	v_cndmask_b32_e64 v215, 0, v215, s[0:1]
	v_cndmask_b32_e64 v65, 0, v216, s[24:25]
	v_cndmask_b32_e64 v64, 0, v217, s[24:25]
	v_lshlrev_b32_e32 v53, 16, v65
	v_lshlrev_b32_e32 v52, 16, v212
	v_pk_mul_f32 v[52:53], v[78:79], v[52:53]
	v_cndmask_b32_e64 v218, 0, v218, s[24:25]
	v_add_f32_e32 v48, v48, v52
	v_add_f32_e32 v48, v48, v53
	v_and_b32_e32 v53, 0xffff0000, v65
	v_and_b32_e32 v52, 0xffff0000, v212
	v_pk_mul_f32 v[44:45], v[44:45], v[52:53]
	v_cndmask_b32_e64 v219, 0, v219, s[24:25]
	v_add_f32_e32 v44, v49, v44
	v_add_f32_e32 v49, v44, v45
	v_lshlrev_b32_e32 v45, 16, v64
	v_lshlrev_b32_e32 v44, 16, v213
	v_pk_mul_f32 v[44:45], v[80:81], v[44:45]
	s_nop 0
	v_add_f32_e32 v44, v50, v44
	v_add_f32_e32 v50, v44, v45
	v_and_b32_e32 v45, 0xffff0000, v64
	v_and_b32_e32 v44, 0xffff0000, v213
	v_pk_mul_f32 v[44:45], v[46:47], v[44:45]
	s_nop 0
	v_add_f32_e32 v44, v51, v44
	v_add_f32_e32 v46, v44, v45
	v_lshlrev_b32_e32 v45, 16, v218
	v_lshlrev_b32_e32 v44, 16, v214
	v_pk_mul_f32 v[44:45], v[82:83], v[44:45]
	s_nop 0
	v_add_f32_e32 v40, v40, v44
	v_add_f32_e32 v47, v40, v45
	v_and_b32_e32 v45, 0xffff0000, v218
	v_and_b32_e32 v44, 0xffff0000, v214
	v_pk_mul_f32 v[36:37], v[36:37], v[44:45]
	v_and_b32_e32 v45, 0xffff0000, v219
	v_add_f32_e32 v36, v41, v36
	v_add_f32_e32 v40, v36, v37
	v_lshlrev_b32_e32 v37, 16, v219
	v_lshlrev_b32_e32 v36, 16, v215
	v_pk_mul_f32 v[36:37], v[84:85], v[36:37]
	v_and_b32_e32 v44, 0xffff0000, v215
	v_add_f32_e32 v36, v42, v36
	v_pk_mul_f32 v[38:39], v[38:39], v[44:45]
	v_add_f32_e32 v37, v36, v37
	v_add_f32_e32 v36, v43, v38
	v_add_f32_e32 v36, v36, v39
	v_cndmask_b32_e64 v41, 0, v223, s[26:27]
	v_cndmask_b32_e64 v51, 0, v222, s[26:27]
	v_cndmask_b32_e64 v52, 0, v221, s[26:27]
	v_cndmask_b32_e64 v53, 0, v220, s[26:27]
	v_lshlrev_b32_e32 v38, 16, v53
	v_cndmask_b32_e64 v224, 0, v224, s[10:11]
	v_lshlrev_b32_e32 v39, 16, v224
	v_pk_mul_f32 v[38:39], v[120:121], v[38:39]
	v_cndmask_b32_e64 v225, 0, v225, s[10:11]
	v_add_f32_e32 v38, v48, v38
	v_add_f32_e32 v48, v38, v39
	v_and_b32_e32 v39, 0xffff0000, v224
	v_and_b32_e32 v38, 0xffff0000, v53
	v_pk_mul_f32 v[32:33], v[32:33], v[38:39]
	v_cndmask_b32_e64 v226, 0, v226, s[10:11]
	v_add_f32_e32 v32, v49, v32
	v_add_f32_e32 v38, v32, v33
	v_lshlrev_b32_e32 v33, 16, v225
	v_lshlrev_b32_e32 v32, 16, v52
	v_pk_mul_f32 v[32:33], v[118:119], v[32:33]
	v_cndmask_b32_e64 v227, 0, v227, s[10:11]
	v_add_f32_e32 v32, v50, v32
	v_add_f32_e32 v39, v32, v33
	v_and_b32_e32 v33, 0xffff0000, v225
	v_and_b32_e32 v32, 0xffff0000, v52
	v_pk_mul_f32 v[32:33], v[34:35], v[32:33]
	s_nop 0
	v_add_f32_e32 v32, v46, v32
	v_add_f32_e32 v34, v32, v33
	v_lshlrev_b32_e32 v33, 16, v226
	v_lshlrev_b32_e32 v32, 16, v51
	v_pk_mul_f32 v[32:33], v[86:87], v[32:33]
	s_nop 0
	v_add_f32_e32 v32, v47, v32
	v_add_f32_e32 v35, v32, v33
	v_and_b32_e32 v33, 0xffff0000, v226
	v_and_b32_e32 v32, 0xffff0000, v51
	v_pk_mul_f32 v[28:29], v[28:29], v[32:33]
	s_nop 0
	v_add_f32_e32 v28, v40, v28
	v_add_f32_e32 v32, v28, v29
	v_lshlrev_b32_e32 v29, 16, v227
	v_lshlrev_b32_e32 v28, 16, v41
	v_pk_mul_f32 v[28:29], v[74:75], v[28:29]
	s_nop 0
	v_add_f32_e32 v28, v37, v28
	v_add_f32_e32 v33, v28, v29
	v_and_b32_e32 v29, 0xffff0000, v227
	v_and_b32_e32 v28, 0xffff0000, v41
	v_pk_mul_f32 v[28:29], v[30:31], v[28:29]
	v_cvt_pk_bf16_f32 v30, v35, v32
	s_nop 0
	v_add_f32_e32 v28, v36, v28
	v_add_f32_e32 v31, v28, v29
	v_cvt_pk_bf16_f32 v28, v48, v38
	v_cvt_pk_bf16_f32 v29, v39, v34
	v_cvt_pk_bf16_f32 v31, v33, v31
	s_lshl_b64 s[80:81], s[80:81], 14
	v_lshl_add_u64 v[120:121], v[100:101], 0, s[78:79]
	v_lshl_add_u64 v[122:123], v[102:103], 0, s[78:79]
	v_lshl_add_u64 v[124:125], v[104:105], 0, s[78:79]
	v_lshl_add_u64 v[126:127], v[106:107], 0, s[78:79]
	v_lshl_add_u64 v[128:129], v[108:109], 0, s[78:79]
	v_readlane_b32 s78, v255, 2
	s_add_u32 s78, s78, s54
	v_readlane_b32 s79, v255, 4
	v_and_or_b32 v32, v202, 64, v92
	s_addc_u32 s79, s79, s55
	v_lshl_or_b32 v184, v32, 2, 60
	v_lshl_add_u64 v[32:33], v[110:111], 0, s[54:55]
	s_add_u32 s54, s68, s54
	s_addc_u32 s55, s69, s55
	v_lshl_add_u64 v[118:119], v[116:117], 0, s[82:83]
	v_lshl_add_u64 v[130:131], s[78:79], 2, v[90:91]
	v_lshl_add_u64 v[132:133], v[32:33], 1, s[66:67]
	v_lshl_add_u64 v[134:135], s[54:55], 1, v[112:113]
	v_lshl_add_u64 v[136:137], v[114:115], 0, s[80:81]
	s_mov_b64 s[78:79], 0
	s_branch .LBB0_195
